# v64 + O3 kv-up epilogue: V^T transposed through wave-private LDS and stored as 16-byte chunks (was 32 two-byte stores per lane)
# speedup vs baseline: 1.0103x; 1.0051x over previous
.LBB0_445:
	s_or_b64 exec, exec, s[2:3]
	v_lshlrev_b32_e32 v128, 1, v128
	v_mul_f32_e32 v56, v5, v86
	v_mul_f32_e32 v57, v4, v86
	v_mul_f32_e32 v58, v3, v86
	v_mul_f32_e32 v59, v2, v86
	v_mul_f32_e32 v60, v1, v86
	v_mul_f32_e32 v61, v0, v86
	v_cvt_pk_bf16_f32 v0, v45, v33
	v_cvt_pk_bf16_f32 v1, v35, v39
	v_cvt_pk_bf16_f32 v2, v41, v43
	v_cvt_pk_bf16_f32 v3, v51, v37
	v_lshl_add_u64 v[4:5], v[84:85], 0, v[128:129]
	v_lshlrev_b32_e32 v46, 2, v87
	global_store_dwordx4 v[4:5], v[0:3], off offset:128
	v_or_b32_e32 v47, 8, v46
	v_mul_f32_e32 v6, v6, v86
	v_cvt_pk_bf16_f32 v0, v44, v32
	v_cvt_pk_bf16_f32 v1, v34, v38
	v_cvt_pk_bf16_f32 v2, v40, v42
	v_cvt_pk_bf16_f32 v3, v50, v36
	global_store_dwordx4 v[4:5], v[0:3], off offset:160
	v_mul_f32_e32 v7, v7, v86
	v_or_b32_e32 v48, 16, v46
	v_mul_u32_u24_e32 v0, v82, v46
	v_lshlrev_b32_e32 v128, 1, v0
	v_lshl_add_u64 v[0:1], v[80:81], 0, v[128:129]
	v_cvt_pk_bf16_f32 v2, v61, s0
	v_and_b32_e32 v240, 31, v155
	v_lshrrev_b32_e32 v239, 6, v155
	v_mul_u32_u24_e32 v239, 0x1400, v239
	v_add_u32_e32 v239, 0xc000, v239
	v_bfe_u32 v246, v155, 5, 1
	v_mul_u32_u24_e32 v246, 0x140, v246
	v_lshl_add_u32 v238, v240, 1, v239
	v_add_u32_e32 v238, v238, v246
	v_bfe_u32 v246, v155, 2, 4
	v_mul_u32_u24_e32 v247, 0x50, v246
	v_add_u32_e32 v239, v239, v247
	v_mul_u32_u24_e32 v246, v82, v246
	v_and_b32_e32 v247, 3, v155
	v_lshl_add_u32 v239, v247, 4, v239
	v_lshlrev_b32_e32 v247, 4, v247
	v_lshl_add_u32 v246, v246, 1, v247
	v_lshlrev_b32_e32 v240, 1, v240
	v_sub_u32_e32 v246, v246, v240
	v_ashrrev_i32_e32 v247, 31, v246
	v_lshl_add_u64 v[244:245], v[80:81], 0, v[246:247]
	v_lshlrev_b32_e32 v246, 5, v82
	v_mov_b32_e32 v247, 0
	ds_write_b16 v238, v2
	v_or_b32_e32 v0, 1, v46
	v_mul_u32_u24_e32 v0, v82, v0
	v_lshlrev_b32_e32 v128, 1, v0
	v_lshl_add_u64 v[0:1], v[80:81], 0, v[128:129]
	v_cvt_pk_bf16_f32 v2, v60, s0
	ds_write_b16 v238, v2 offset:80
	v_or_b32_e32 v0, 2, v46
	v_mul_u32_u24_e32 v0, v82, v0
	v_lshlrev_b32_e32 v128, 1, v0
	v_lshl_add_u64 v[0:1], v[80:81], 0, v[128:129]
	v_cvt_pk_bf16_f32 v2, v59, s0
	ds_write_b16 v238, v2 offset:160
	v_or_b32_e32 v0, 3, v46
	v_mul_u32_u24_e32 v0, v82, v0
	v_lshlrev_b32_e32 v128, 1, v0
	v_lshl_add_u64 v[0:1], v[80:81], 0, v[128:129]
	v_cvt_pk_bf16_f32 v2, v58, s0
	ds_write_b16 v238, v2 offset:240
	v_mul_u32_u24_e32 v0, v82, v47
	v_lshlrev_b32_e32 v128, 1, v0
	v_lshl_add_u64 v[0:1], v[80:81], 0, v[128:129]
	v_cvt_pk_bf16_f32 v2, v57, s0
	ds_write_b16 v238, v2 offset:640
	v_or_b32_e32 v0, 9, v46
	v_mul_u32_u24_e32 v0, v82, v0
	v_lshlrev_b32_e32 v128, 1, v0
	v_lshl_add_u64 v[0:1], v[80:81], 0, v[128:129]
	v_cvt_pk_bf16_f32 v2, v56, s0
	ds_write_b16 v238, v2 offset:720
	v_or_b32_e32 v0, 10, v46
	v_mul_u32_u24_e32 v0, v82, v0
	v_lshlrev_b32_e32 v128, 1, v0
	v_lshl_add_u64 v[0:1], v[80:81], 0, v[128:129]
	v_cvt_pk_bf16_f32 v2, v6, s0
	ds_write_b16 v238, v2 offset:800
	v_or_b32_e32 v0, 11, v46
	v_mul_u32_u24_e32 v0, v82, v0
	v_lshlrev_b32_e32 v128, 1, v0
	v_lshl_add_u64 v[0:1], v[80:81], 0, v[128:129]
	v_cvt_pk_bf16_f32 v2, v7, s0
	ds_write_b16 v238, v2 offset:880
	v_mul_u32_u24_e32 v0, v82, v48
	v_mul_f32_e32 v8, v8, v86
	v_lshlrev_b32_e32 v128, 1, v0
	v_lshl_add_u64 v[0:1], v[80:81], 0, v[128:129]
	v_cvt_pk_bf16_f32 v2, v8, s0
	ds_write_b16 v238, v2 offset:1280
	v_or_b32_e32 v0, 17, v46
	v_mul_u32_u24_e32 v0, v82, v0
	v_mul_f32_e32 v9, v9, v86
	v_lshlrev_b32_e32 v128, 1, v0
	v_lshl_add_u64 v[0:1], v[80:81], 0, v[128:129]
	v_cvt_pk_bf16_f32 v2, v9, s0
	ds_write_b16 v238, v2 offset:1360
	v_or_b32_e32 v0, 18, v46
	v_mul_u32_u24_e32 v0, v82, v0
	v_mul_f32_e32 v10, v10, v86
	v_lshlrev_b32_e32 v128, 1, v0
	v_lshl_add_u64 v[0:1], v[80:81], 0, v[128:129]
	v_cvt_pk_bf16_f32 v2, v10, s0
	ds_write_b16 v238, v2 offset:1440
	v_or_b32_e32 v0, 19, v46
	v_mul_u32_u24_e32 v0, v82, v0
	v_mul_f32_e32 v11, v11, v86
	v_lshlrev_b32_e32 v128, 1, v0
	v_or_b32_e32 v49, 24, v46
	v_lshl_add_u64 v[0:1], v[80:81], 0, v[128:129]
	v_cvt_pk_bf16_f32 v2, v11, s0
	ds_write_b16 v238, v2 offset:1520
	v_mul_u32_u24_e32 v0, v82, v49
	v_mul_f32_e32 v12, v12, v86
	v_lshlrev_b32_e32 v128, 1, v0
	v_lshl_add_u64 v[0:1], v[80:81], 0, v[128:129]
	v_cvt_pk_bf16_f32 v2, v12, s0
	ds_write_b16 v238, v2 offset:1920
	v_or_b32_e32 v0, 25, v46
	v_mul_u32_u24_e32 v0, v82, v0
	v_mul_f32_e32 v13, v13, v86
	v_lshlrev_b32_e32 v128, 1, v0
	v_lshl_add_u64 v[0:1], v[80:81], 0, v[128:129]
	v_cvt_pk_bf16_f32 v2, v13, s0
	ds_write_b16 v238, v2 offset:2000
	v_or_b32_e32 v0, 26, v46
	v_mul_u32_u24_e32 v0, v82, v0
	v_mul_f32_e32 v14, v14, v86
	v_lshlrev_b32_e32 v128, 1, v0
	v_lshl_add_u64 v[0:1], v[80:81], 0, v[128:129]
	v_cvt_pk_bf16_f32 v2, v14, s0
	ds_write_b16 v238, v2 offset:2080
	v_or_b32_e32 v0, 27, v46
	v_mul_u32_u24_e32 v0, v82, v0
	v_mul_f32_e32 v15, v15, v86
	v_lshlrev_b32_e32 v128, 1, v0
	v_or_b32_e32 v52, 32, v46
	v_lshl_add_u64 v[0:1], v[80:81], 0, v[128:129]
	v_cvt_pk_bf16_f32 v2, v15, s0
	ds_write_b16 v238, v2 offset:2160
	v_mul_u32_u24_e32 v0, v82, v52
	v_mul_f32_e32 v16, v16, v86
	v_lshlrev_b32_e32 v128, 1, v0
	v_lshl_add_u64 v[0:1], v[80:81], 0, v[128:129]
	v_cvt_pk_bf16_f32 v2, v16, s0
	ds_write_b16 v238, v2 offset:2560
	v_or_b32_e32 v0, 33, v46
	v_mul_u32_u24_e32 v0, v82, v0
	v_mul_f32_e32 v17, v17, v86
	v_lshlrev_b32_e32 v128, 1, v0
	v_lshl_add_u64 v[0:1], v[80:81], 0, v[128:129]
	v_cvt_pk_bf16_f32 v2, v17, s0
	ds_write_b16 v238, v2 offset:2640
	v_or_b32_e32 v0, 34, v46
	v_mul_u32_u24_e32 v0, v82, v0
	v_mul_f32_e32 v18, v18, v86
	v_lshlrev_b32_e32 v128, 1, v0
	v_lshl_add_u64 v[0:1], v[80:81], 0, v[128:129]
	v_cvt_pk_bf16_f32 v2, v18, s0
	ds_write_b16 v238, v2 offset:2720
	v_or_b32_e32 v0, 35, v46
	v_mul_u32_u24_e32 v0, v82, v0
	v_mul_f32_e32 v19, v19, v86
	v_lshlrev_b32_e32 v128, 1, v0
	v_or_b32_e32 v53, 40, v46
	v_lshl_add_u64 v[0:1], v[80:81], 0, v[128:129]
	v_cvt_pk_bf16_f32 v2, v19, s0
	ds_write_b16 v238, v2 offset:2800
	v_mul_u32_u24_e32 v0, v82, v53
	v_mul_f32_e32 v20, v20, v86
	v_lshlrev_b32_e32 v128, 1, v0
	v_lshl_add_u64 v[0:1], v[80:81], 0, v[128:129]
	v_cvt_pk_bf16_f32 v2, v20, s0
	ds_write_b16 v238, v2 offset:3200
	v_or_b32_e32 v0, 41, v46
	v_mul_u32_u24_e32 v0, v82, v0
	v_mul_f32_e32 v21, v21, v86
	v_lshlrev_b32_e32 v128, 1, v0
	v_lshl_add_u64 v[0:1], v[80:81], 0, v[128:129]
	v_cvt_pk_bf16_f32 v2, v21, s0
	ds_write_b16 v238, v2 offset:3280
	v_or_b32_e32 v0, 42, v46
	v_mul_u32_u24_e32 v0, v82, v0
	v_mul_f32_e32 v22, v22, v86
	v_lshlrev_b32_e32 v128, 1, v0
	v_lshl_add_u64 v[0:1], v[80:81], 0, v[128:129]
	v_cvt_pk_bf16_f32 v2, v22, s0
	ds_write_b16 v238, v2 offset:3360
	v_or_b32_e32 v0, 43, v46
	v_mul_u32_u24_e32 v0, v82, v0
	v_mul_f32_e32 v23, v23, v86
	v_lshlrev_b32_e32 v128, 1, v0
	v_or_b32_e32 v54, 48, v46
	v_lshl_add_u64 v[0:1], v[80:81], 0, v[128:129]
	v_cvt_pk_bf16_f32 v2, v23, s0
	ds_write_b16 v238, v2 offset:3440
	v_mul_u32_u24_e32 v0, v82, v54
	v_mul_f32_e32 v24, v24, v86
	v_lshlrev_b32_e32 v128, 1, v0
	v_lshl_add_u64 v[0:1], v[80:81], 0, v[128:129]
	v_cvt_pk_bf16_f32 v2, v24, s0
	ds_write_b16 v238, v2 offset:3840
	v_or_b32_e32 v0, 49, v46
	v_mul_u32_u24_e32 v0, v82, v0
	v_mul_f32_e32 v25, v25, v86
	v_lshlrev_b32_e32 v128, 1, v0
	v_lshl_add_u64 v[0:1], v[80:81], 0, v[128:129]
	v_cvt_pk_bf16_f32 v2, v25, s0
	ds_write_b16 v238, v2 offset:3920
	v_or_b32_e32 v0, 50, v46
	v_mul_u32_u24_e32 v0, v82, v0
	v_mul_f32_e32 v26, v26, v86
	v_lshlrev_b32_e32 v128, 1, v0
	v_lshl_add_u64 v[0:1], v[80:81], 0, v[128:129]
	v_cvt_pk_bf16_f32 v2, v26, s0
	ds_write_b16 v238, v2 offset:4000
	v_or_b32_e32 v0, 51, v46
	v_mul_u32_u24_e32 v0, v82, v0
	v_mul_f32_e32 v27, v27, v86
	v_lshlrev_b32_e32 v128, 1, v0
	v_or_b32_e32 v55, 56, v46
	v_lshl_add_u64 v[0:1], v[80:81], 0, v[128:129]
	v_cvt_pk_bf16_f32 v2, v27, s0
	ds_write_b16 v238, v2 offset:4080
	v_mul_u32_u24_e32 v0, v82, v55
	v_mul_f32_e32 v28, v28, v86
	v_lshlrev_b32_e32 v128, 1, v0
	v_lshl_add_u64 v[0:1], v[80:81], 0, v[128:129]
	v_cvt_pk_bf16_f32 v2, v28, s0
	ds_write_b16 v238, v2 offset:4480
	v_or_b32_e32 v0, 57, v46
	v_mul_u32_u24_e32 v0, v82, v0
	v_mul_f32_e32 v29, v29, v86
	v_lshlrev_b32_e32 v128, 1, v0
	v_lshl_add_u64 v[0:1], v[80:81], 0, v[128:129]
	v_cvt_pk_bf16_f32 v2, v29, s0
	ds_write_b16 v238, v2 offset:4560
	v_or_b32_e32 v0, 58, v46
	v_mul_u32_u24_e32 v0, v82, v0
	v_mul_f32_e32 v30, v30, v86
	v_lshlrev_b32_e32 v128, 1, v0
	v_lshl_add_u64 v[0:1], v[80:81], 0, v[128:129]
	v_cvt_pk_bf16_f32 v2, v30, s0
	ds_write_b16 v238, v2 offset:4640
	v_or_b32_e32 v0, 59, v46
	v_mul_u32_u24_e32 v0, v82, v0
	v_mul_f32_e32 v31, v31, v86
	v_lshlrev_b32_e32 v128, 1, v0
	v_lshl_add_u64 v[0:1], v[80:81], 0, v[128:129]
	v_cvt_pk_bf16_f32 v2, v31, s0
	ds_write_b16 v238, v2 offset:4720
	s_waitcnt lgkmcnt(0)
	ds_read_b128 v[230:233], v239
	ds_read_b128 v[234:237], v239 offset:1280
	s_waitcnt lgkmcnt(1)
	global_store_dwordx4 v[244:245], v[230:233], off
	v_lshl_add_u64 v[244:245], v[244:245], 0, v[246:247]
	s_nop 4
	ds_read_b128 v[230:233], v239 offset:2560
	s_waitcnt lgkmcnt(1)
	global_store_dwordx4 v[244:245], v[234:237], off
	v_lshl_add_u64 v[244:245], v[244:245], 0, v[246:247]
	s_nop 4
	ds_read_b128 v[234:237], v239 offset:3840
	s_waitcnt lgkmcnt(1)
	global_store_dwordx4 v[244:245], v[230:233], off
	v_lshl_add_u64 v[244:245], v[244:245], 0, v[246:247]
	s_waitcnt lgkmcnt(0)
	global_store_dwordx4 v[244:245], v[234:237], off
